# scan constants prologue: 7 loads issued together instead of 4 serialized round trips
# baseline (speedup 1.0000x reference)
; __device__ __forceinline__ void scan_half(const Params& p, LAS unsigned char* lds, int pi, int rh, int pass) {
;     ...
;     if (tid < 64) { CST[tid] = ((const float*)p.in[I_W0])[colg + tid]; CST[64 + tid] = ((const float*)p.in[I_A0])[colg + tid]; CST[128 + tid] = ((const float*)p.in[I_KK])[colg + tid]; CST[192 + tid] = ((const float*)p.in[I_KA])[colg + tid]; CST[256 + tid] = ((const float*)p.in[I_RK])[colg + tid];
;                     CST[320 + tid] = ((const float*)p.in[I_LNG])[colg + tid]; CST[384 + tid] = ((const float*)p.in[I_LNB])[colg + tid]; }
.LBB0_981:
	s_mov_b32 s24, s60
	s_mov_b32 s25, s61
	v_mov_b32_e32 v113, v162
	s_lshl_b32 s76, s16, 6
	s_and_b32 s17, s76, 0x7c0
	v_readfirstlane_b32 s30, v113
	v_cmp_gt_i32_e32 vcc, 64, v113
	s_barrier
	s_and_saveexec_b64 s[8:9], vcc
	s_cbranch_execz .LBB0_983
	s_load_dwordx2 s[12:13], s[0:1], 0x98
	s_load_dwordx2 s[14:15], s[0:1], 0xb0
	s_load_dwordx2 s[18:19], s[0:1], 0xe8
	s_waitcnt vmcnt(0)
	v_add_u32_e32 v0, s17, v113
	v_ashrrev_i32_e32 v1, 31, v0
	v_lshlrev_b64 v[0:1], 2, v[0:1]
	v_lshl_add_u32 v2, v113, 2, 0
	v_add_u32_e32 v5, 0x21b00, v2
	s_waitcnt lgkmcnt(0)
	v_lshl_add_u64 v[2:3], s[12:13], 0, v[0:1]
	global_load_dword v4, v[2:3], off
	v_lshl_add_u64 v[2:3], s[14:15], 0, v[0:1]
	global_load_dword v6, v[2:3], off
	v_lshl_add_u64 v[2:3], s[44:45], 0, v[0:1]
	global_load_dword v7, v[2:3], off
	v_lshl_add_u64 v[2:3], s[46:47], 0, v[0:1]
	global_load_dword v8, v[2:3], off
	v_lshl_add_u64 v[2:3], s[48:49], 0, v[0:1]
	global_load_dword v9, v[2:3], off
	v_lshl_add_u64 v[2:3], s[50:51], 0, v[0:1]
	global_load_dword v10, v[2:3], off
	v_lshl_add_u64 v[2:3], s[18:19], 0, v[0:1]
	global_load_dword v11, v[2:3], off
	s_waitcnt vmcnt(0)
	ds_write2st64_b32 v5, v4, v6 offset1:1
	ds_write2st64_b32 v5, v7, v8 offset0:2 offset1:3
	ds_write2st64_b32 v5, v9, v10 offset0:4 offset1:5
	ds_write_b32 v5, v11 offset:1536
